# compute list order: the 64 longest attention units take tickets 0..63, the gate-GEMM units tickets 64..127 (were first)
# speedup vs baseline: 1.0133x; 1.0012x over previous
; #define KPTR(T, ap64, i) ((T*)(__attribute__((address_space(1))) T*)(ap64)[i])
; __global__ void __launch_bounds__(512, 2) mk_fwd(MKArgs args) {
;     ...
;                   __syncthreads();
;                   const unsigned kind = LQ[0], idx = LQ[1];
;                   __syncthreads();
;                   if (kind == 2u) break;
;                   if (kind == 0u) { PHASE_IDS sample_attn_task(l, (int)idx, tid, ldsl + RING_OFF, ws, KPTR(const float, ap, 2), KPTR(const float, ap, 3), (const int*)KPTR(const float, ap, 4), KPTR(const float, ap, 24)); }
;                   else if (idx < (unsigned)(M / 256)) {
;                       pg8::Gemm g{(const bf16_t*)(ws + WS_Y5), (const bf16_t*)(wl + WL_GLU), M, 256, 256}; const pg8::OneUnitPub S{(int)idx, 0, (unsigned*)(ws + WS_CTL) + CW_MX + (l * 64 + (int)idx) * 64};
;                       pg8::EpiGlu E{(const bf16_t*)(ws + WS_Y5), KPTR(const float, ap, 19) + l * 256, (bf16_t*)(ws + WS_MIX)};
;                       pg8::gemm_phase<pg8::EpiGlu, pg8::OneUnitPub, true, true>(ldsl + RING_OFF, g, S, E, wave_s); }
;                   else { const int ia = (int)idx - M / 256, qb = 7 - (ia >> 6), bh = ia & 63;
.LBB0_1262:
	v_mov_b32_e32 v0, s51
	s_waitcnt lgkmcnt(0)
	s_barrier
	ds_read_b32 v0, v0
	s_mov_b64 s[8:9], -1
	s_mov_b64 s[4:5], 0
	s_mov_b64 s[6:7], 0
	s_waitcnt lgkmcnt(0)
	v_readfirstlane_b32 s10, v0
	v_mov_b32_e32 v0, s52
	ds_read_b32 v0, v0
	s_cmp_lt_i32 s10, 2
	s_waitcnt lgkmcnt(0)
	s_barrier
	v_readfirstlane_b32 s79, v0
	s_cmp_eq_u32 s10, 1
	s_cbranch_scc0 .Lq3_noremap
	s_cmpk_gt_u32 s79, 127
	s_cbranch_scc1 .Lq3_noremap
	s_xor_b32 s79, s79, 64
.Lq3_noremap:
	s_cmp_lt_i32 s10, 2
	s_cbranch_scc1 .LBB0_1284
	s_cmp_lg_u32 s10, 2
	s_cselect_b64 s[6:7], -1, 0
	s_cbranch_execz .LBB0_1285
